# DF early half: its four staging LDS-DMA issues moved behind its QK^T MFMAs (its MFMAs reach the matrix pipe ahead of the late half's burst)
# speedup vs baseline: 1.0061x; 1.0061x over previous
.LBB0_437:
	s_mov_b32 s97, s96
	s_waitcnt lgkmcnt(0)
	v_cmp_eq_u64_e64 s[8:9], s[96:97], v[2:3]
	s_and_b64 vcc, exec, s[8:9]
	s_cbranch_vccnz .LBB0_449
	s_cmp_gt_i32 s15, s21
	s_cbranch_scc1 .LBB0_446
	s_add_i32 s8, s13, 0xffff4000
	s_and_b32 s8, s8, 0xc000
	v_add_u32_e32 v0, s8, v221
	v_add_u32_e32 v6, v0, v222
	v_add_u32_e32 v14, v0, v223
	ds_read_b128 v[2:5], v6
	ds_read_b128 v[6:9], v6 offset:4096
	ds_read_b128 v[10:13], v14
	ds_read_b128 v[128:131], v14 offset:4096
	v_add_u32_e32 v14, v0, v224
	v_add_u32_e32 v0, v0, v219
	ds_read_b128 v[132:135], v14
	ds_read_b128 v[136:139], v14 offset:4096
	ds_read_b128 v[144:147], v0
	ds_read_b128 v[148:151], v0 offset:4096
	s_add_i32 s8, s12, s10
	s_lshl_b32 s9, s14, 14
	s_waitcnt lgkmcnt(7)
	v_mfma_f32_32x32x16_bf16 v[96:111], v[2:5], v[112:115], 0
	v_add_u32_e32 v235, s9, v220
	s_waitcnt lgkmcnt(6)
	v_mfma_f32_32x32x16_bf16 v[80:95], v[6:9], v[112:115], 0
	s_waitcnt lgkmcnt(5)
	v_mfma_f32_32x32x16_bf16 v[96:111], v[10:13], v[116:119], v[96:111]
	s_waitcnt lgkmcnt(4)
	v_mfma_f32_32x32x16_bf16 v[80:95], v[128:131], v[116:119], v[80:95]
	ds_read_b64_tr_b16 v[6:7], v235
	ds_read_b64_tr_b16 v[8:9], v235 offset:512
	ds_read_b64_tr_b16 v[2:3], v235 offset:1024
	ds_read_b64_tr_b16 v[4:5], v235 offset:1536
	ds_read_b64_tr_b16 v[140:141], v235 offset:4096
	ds_read_b64_tr_b16 v[142:143], v235 offset:4608
	ds_read_b64_tr_b16 v[128:129], v235 offset:5120
	ds_read_b64_tr_b16 v[130:131], v235 offset:5632
	s_waitcnt lgkmcnt(11)
	v_mfma_f32_32x32x16_bf16 v[96:111], v[132:135], v[120:123], v[96:111]
	s_waitcnt lgkmcnt(10)
	v_mfma_f32_32x32x16_bf16 v[80:95], v[136:139], v[120:123], v[80:95]
	s_waitcnt lgkmcnt(9)
	v_mfma_f32_32x32x16_bf16 v[96:111], v[144:147], v[124:127], v[96:111]
	ds_read_b64_tr_b16 v[136:137], v235 offset:2048
	ds_read_b64_tr_b16 v[138:139], v235 offset:2560
	ds_read_b64_tr_b16 v[10:11], v235 offset:3072
	ds_read_b64_tr_b16 v[12:13], v235 offset:3584
	ds_read_b64_tr_b16 v[144:145], v235 offset:6144
	ds_read_b64_tr_b16 v[146:147], v235 offset:6656
	ds_read_b64_tr_b16 v[132:133], v235 offset:7168
	ds_read_b64_tr_b16 v[134:135], v235 offset:7680
	s_waitcnt lgkmcnt(14)
	v_mfma_f32_32x32x16_bf16 v[80:95], v[148:151], v[124:127], v[80:95]
	s_cmp_lt_i32 s15, 3
	s_cbranch_scc1 .Ldfst_e1
	s_and_b32 s28, s13, 0xc000
	s_cmp_gt_i32 s14, 1
	s_cselect_b32 s29, -2, 3
	s_add_i32 s29, s29, s14
	s_add_i32 s80, s10, -4
	s_lshl_b32 s29, s29, 14
	s_lshl_b64 s[26:27], s[80:81], 14
	v_lshl_add_u64 v[240:241], v[180:181], 0, s[26:27]
	s_add_i32 s28, s76, s28
	s_mov_b32 m0, s28
	s_nop 0
	global_load_lds_dwordx4 v[240:241], off
	v_lshl_add_u64 v[240:241], v[240:241], 0, s[88:89]
	s_addk_i32 s28, 0x2000
	s_mov_b32 m0, s28
	s_nop 0
	global_load_lds_dwordx4 v[240:241], off
	v_lshl_add_u64 v[240:241], v[182:183], 0, s[26:27]
	s_add_i32 s28, s31, s29
	s_mov_b32 m0, s28
	s_nop 0
	global_load_lds_dwordx4 v[240:241], off
	v_lshl_add_u64 v[240:241], v[240:241], 0, s[88:89]
	s_addk_i32 s28, 0x2000
	s_mov_b32 m0, s28
	s_nop 0
	global_load_lds_dwordx4 v[240:241], off
.Ldfst_e1:
	v_add_u32_e32 v0, v233, v218
	v_cvt_f32_i32_e32 v0, v0
	s_cmp_lg_u32 s8, 1
	s_mov_b64 s[8:9], -1
	s_cbranch_scc0 .LBB0_441
	v_add_f32_e32 v14, 0, v96
	v_subrev_f32_e32 v15, s4, v97
	s_nop 4
	v_fma_f32 v186, s2, v196, v80
	v_fma_f32 v187, s3, v197, v81
	v_fma_f32 v184, s2, v226, v98
	v_fma_f32 v185, s3, v227, v99
	v_max_f32_e32 v148, v14, v186
	v_max_f32_e32 v149, v15, v187
	v_fma_f32 v188, s2, v152, v82
	v_fma_f32 v189, s3, v153, v83
	v_max3_f32 v148, v148, s82, v149
	v_max_f32_e32 v149, v184, v188
	v_max_f32_e32 v150, v185, v189
	v_fma_f32 v190, s2, v154, v100
	v_fma_f32 v191, s3, v155, v101
	v_fma_f32 v192, s2, v156, v84
	v_fma_f32 v193, s3, v157, v85
	v_max3_f32 v148, v148, v149, v150
	v_max_f32_e32 v149, v190, v192
	v_max_f32_e32 v150, v191, v193
	v_fma_f32 v194, s2, v158, v102
	v_fma_f32 v195, s3, v159, v103
	v_fma_f32 v198, s2, v160, v86
	v_fma_f32 v199, s3, v161, v87
	v_max3_f32 v148, v148, v149, v150
	v_max_f32_e32 v149, v194, v198
	v_max_f32_e32 v150, v195, v199
	v_fma_f32 v200, s2, v162, v104
	v_fma_f32 v201, s3, v163, v105
	v_fma_f32 v202, s2, v164, v88
	v_fma_f32 v203, s3, v165, v89
	v_max3_f32 v148, v148, v149, v150
	v_max_f32_e32 v149, v200, v202
	v_max_f32_e32 v150, v201, v203
	v_fma_f32 v204, s2, v166, v106
	v_fma_f32 v205, s3, v167, v107
	v_fma_f32 v206, s2, v168, v90
	v_fma_f32 v207, s3, v169, v91
	v_max3_f32 v148, v148, v149, v150
	v_max_f32_e32 v149, v204, v206
	v_max_f32_e32 v150, v205, v207
	v_fma_f32 v208, s2, v170, v108
	v_fma_f32 v209, s3, v171, v109
	v_fma_f32 v210, s2, v172, v92
	v_fma_f32 v211, s3, v173, v93
	v_max3_f32 v148, v148, v149, v150
	v_max_f32_e32 v149, v208, v210
	v_max_f32_e32 v150, v209, v211
	v_fma_f32 v212, s2, v174, v110
	v_fma_f32 v213, s3, v175, v111
	v_fma_f32 v214, s2, v176, v94
	v_fma_f32 v215, s3, v177, v95
	v_max3_f32 v148, v148, v149, v150
	v_max_f32_e32 v149, v212, v214
	v_max_f32_e32 v150, v213, v215
	v_max3_f32 v237, v148, v149, v150
	v_mul_f32_e32 v236, s4, v0
	s_mov_b64 s[8:9], 0

.LBB0_446:
	s_cmp_lt_i32 s15, 3
	s_cbranch_scc1 .Ldfst_e2
	s_and_b32 s28, s13, 0xc000
	s_cmp_gt_i32 s14, 1
	s_cselect_b32 s29, -2, 3
	s_add_i32 s29, s29, s14
	s_add_i32 s80, s10, -4
	s_lshl_b32 s29, s29, 14
	s_lshl_b64 s[26:27], s[80:81], 14
	v_lshl_add_u64 v[240:241], v[180:181], 0, s[26:27]
	s_add_i32 s28, s76, s28
	s_mov_b32 m0, s28
	s_nop 0
	global_load_lds_dwordx4 v[240:241], off
	v_lshl_add_u64 v[240:241], v[240:241], 0, s[88:89]
	s_addk_i32 s28, 0x2000
	s_mov_b32 m0, s28
	s_nop 0
	global_load_lds_dwordx4 v[240:241], off
	v_lshl_add_u64 v[240:241], v[182:183], 0, s[26:27]
	s_add_i32 s28, s31, s29
	s_mov_b32 m0, s28
	s_nop 0
	global_load_lds_dwordx4 v[240:241], off
	v_lshl_add_u64 v[240:241], v[240:241], 0, s[88:89]
	s_addk_i32 s28, 0x2000
	s_mov_b32 m0, s28
	s_nop 0
	global_load_lds_dwordx4 v[240:241], off
